# v24 plus static priority raise for waves 4-7 in the gate-up K-loop with the per-segment s_setprio flips removed
# baseline (speedup 1.0000x reference)
.LBB0_283:
	s_add_u32 s14, s14, 0x1ca00000
	s_addc_u32 s15, s15, 0
	s_add_i32 s48, s34, 0x18000
	s_or_b32 s19, s79, 0x80
	s_mov_b32 m0, s48
	s_add_i32 s49, s34, 0x1a000
	s_waitcnt vmcnt(2)
	s_barrier
	buffer_load_dwordx4 v154, s[36:39], s19 offen lds
	s_mov_b32 m0, s49
	s_add_i32 s51, s34, 0x8000
	buffer_load_dwordx4 v156, s[36:39], s19 offen lds
	s_or_b32 s19, s78, 0x80
	s_mov_b32 m0, s51
	s_add_i32 s52, s34, 0xa000
	buffer_load_dwordx4 v1, s[28:31], s19 offen lds
	s_mov_b32 m0, s52
	s_add_i32 s53, s34, 0x1c000
	buffer_load_dwordx4 v155, s[28:31], s19 offen lds
	s_or_b32 s19, s79, 0x40080
	s_mov_b32 m0, s53
	s_add_i32 s55, s34, 0x1e000
	buffer_load_dwordx4 v154, s[36:39], s19 offen lds
	s_mov_b32 m0, s55
	v_lshrrev_b32_e32 v3, 1, v2
	buffer_load_dwordx4 v156, s[36:39], s19 offen lds
	v_and_b32_e32 v159, 24, v3
	s_lshl_b32 s17, s17, 5
	v_and_b32_e32 v157, 15, v2
	v_lshlrev_b32_e32 v3, 1, v159
	v_lshlrev_b32_e32 v6, 2, v2
	s_and_b32 s57, s17, 0x60
	s_lshl_b32 s56, s18, 6
	v_lshl_or_b32 v3, v157, 6, v3
	s_lshl_b32 s18, s18, 13
	v_and_b32_e32 v6, 32, v6
	s_lshl_b32 s17, s57, 7
	v_bitop3_b32 v8, v3, s18, v6 bitop3:0xde
	v_bitop3_b32 v9, s17, v3, v6 bitop3:0xf6
	s_waitcnt vmcnt(6)
	s_add_i32 s59, s34, 0xc000
	v_mov_b32_e32 v3, v223
	s_cmpk_lt_u32 s16, 0x100
	v_mov_b32_e32 v6, v2
	v_lshl_add_u64 v[130:131], v[2:3], 2, v[4:5]
	v_add_u32_e32 v2, 0, v9
	v_or_b32_e32 v158, s56, v157
	s_cselect_b64 s[16:17], -1, 0
	s_add_i32 s60, s34, 0xe000
	s_ashr_i32 s61, s20, 31
	v_lshl_add_u64 v[132:133], v[6:7], 2, s[8:9]
	v_or_b32_e32 v160, s57, v159
	s_mov_b32 s77, 0
	v_add_u32_e32 v161, 0x10000, v2
	v_add_u32_e32 v162, 0x14000, v2
	v_add_u32_e32 v163, 0, v8
	v_add_u32_e32 v164, 0x18000, v2
	v_add_u32_e32 v165, 0x1c000, v2
	s_barrier
	s_cmp_lg_u64 s[12:13], 0
	s_cbranch_scc0 .Lprio_skip_gu
	s_setprio 1
.Lprio_skip_gu:
	s_branch .LBB0_286
.LBB0_284:
	s_mov_b64 s[18:19], 0

.LBB0_289:
	ds_read_b128 v[134:137], v161
	ds_read_b128 v[138:141], v161 offset:1024
	ds_read_b128 v[142:145], v161 offset:2048
	ds_read_b128 v[146:149], v161 offset:3072
	ds_read_b128 v[150:153], v162
	ds_read_b128 v[166:169], v162 offset:1024
	ds_read_b128 v[170:173], v162 offset:2048
	ds_read_b128 v[174:177], v162 offset:3072
	s_add_i32 s39, s78, 0xfffc0080
	s_cmp_eq_u32 s80, 12
	s_cselect_b32 s88, s18, s39
	s_cselect_b32 s83, s19, s79
	s_or_b32 s82, s88, 0x80
	s_mov_b32 m0, s59
	ds_read_b128 v[178:181], v163
	ds_read_b128 v[182:185], v163 offset:1024
	ds_read_b128 v[186:189], v163 offset:2048
	ds_read_b128 v[190:193], v163 offset:3072
	ds_read_b128 v[194:197], v163 offset:4096
	ds_read_b128 v[198:201], v163 offset:5120
	ds_read_b128 v[202:205], v163 offset:6144
	ds_read_b128 v[206:209], v163 offset:7168
	buffer_load_dwordx4 v1, s[28:31], s78 offen lds
	s_mov_b32 m0, s60
	s_nop 0
	buffer_load_dwordx4 v155, s[28:31], s78 offen lds
	s_waitcnt vmcnt(8)
	s_waitcnt lgkmcnt(0)
	s_barrier
	s_waitcnt lgkmcnt(0)
	v_mfma_i32_16x16x64_i8 v[126:129], v[134:137], v[178:181], v[126:129]
	v_mfma_i32_16x16x64_i8 v[122:125], v[142:145], v[178:181], v[122:125]
	v_mfma_i32_16x16x64_i8 v[110:113], v[134:137], v[186:189], v[110:113]
	v_mfma_i32_16x16x64_i8 v[106:109], v[142:145], v[186:189], v[106:109]
	v_mfma_i32_16x16x64_i8 v[94:97], v[134:137], v[194:197], v[94:97]
	v_mfma_i32_16x16x64_i8 v[90:93], v[142:145], v[194:197], v[90:93]
	v_mfma_i32_16x16x64_i8 v[78:81], v[134:137], v[202:205], v[78:81]
	v_mfma_i32_16x16x64_i8 v[74:77], v[142:145], v[202:205], v[74:77]
	v_mfma_i32_16x16x64_i8 v[126:129], v[138:141], v[182:185], v[126:129]
	v_mfma_i32_16x16x64_i8 v[122:125], v[146:149], v[182:185], v[122:125]
	v_mfma_i32_16x16x64_i8 v[110:113], v[138:141], v[190:193], v[110:113]
	v_mfma_i32_16x16x64_i8 v[106:109], v[146:149], v[190:193], v[106:109]
	v_mfma_i32_16x16x64_i8 v[94:97], v[138:141], v[198:201], v[94:97]
	v_mfma_i32_16x16x64_i8 v[90:93], v[146:149], v[198:201], v[90:93]
	v_mfma_i32_16x16x64_i8 v[78:81], v[138:141], v[206:209], v[78:81]
	v_mfma_i32_16x16x64_i8 v[74:77], v[146:149], v[206:209], v[74:77]
	v_mfma_i32_16x16x64_i8 v[118:121], v[150:153], v[178:181], v[118:121]
	v_mfma_i32_16x16x64_i8 v[114:117], v[170:173], v[178:181], v[114:117]
	v_mfma_i32_16x16x64_i8 v[102:105], v[150:153], v[186:189], v[102:105]
	v_mfma_i32_16x16x64_i8 v[98:101], v[170:173], v[186:189], v[98:101]
	v_mfma_i32_16x16x64_i8 v[86:89], v[150:153], v[194:197], v[86:89]
	v_mfma_i32_16x16x64_i8 v[82:85], v[170:173], v[194:197], v[82:85]
	v_mfma_i32_16x16x64_i8 v[70:73], v[150:153], v[202:205], v[70:73]
	v_mfma_i32_16x16x64_i8 v[66:69], v[170:173], v[202:205], v[66:69]
	v_mfma_i32_16x16x64_i8 v[118:121], v[166:169], v[182:185], v[118:121]
	v_mfma_i32_16x16x64_i8 v[114:117], v[174:177], v[182:185], v[114:117]
	v_mfma_i32_16x16x64_i8 v[102:105], v[166:169], v[190:193], v[102:105]
	v_mfma_i32_16x16x64_i8 v[98:101], v[174:177], v[190:193], v[98:101]
	v_mfma_i32_16x16x64_i8 v[86:89], v[166:169], v[198:201], v[86:89]
	v_mfma_i32_16x16x64_i8 v[82:85], v[174:177], v[198:201], v[82:85]
	v_mfma_i32_16x16x64_i8 v[70:73], v[166:169], v[206:209], v[70:73]
	v_mfma_i32_16x16x64_i8 v[66:69], v[174:177], v[206:209], v[66:69]
	s_barrier
	s_mov_b32 m0, s35
	s_mov_b32 s39, s31
	ds_read_b128 v[178:181], v163 offset:16384
	ds_read_b128 v[182:185], v163 offset:17408
	ds_read_b128 v[186:189], v163 offset:18432
	ds_read_b128 v[190:193], v163 offset:19456
	ds_read_b128 v[194:197], v163 offset:20480
	ds_read_b128 v[198:201], v163 offset:21504
	ds_read_b128 v[202:205], v163 offset:22528
	ds_read_b128 v[206:209], v163 offset:23552
	buffer_load_dwordx4 v154, s[36:39], s83 offen lds
	s_mov_b32 m0, s40
	s_add_i32 s89, s83, 0x40000
	buffer_load_dwordx4 v156, s[36:39], s83 offen lds
	s_mov_b32 m0, s41
	s_nop 0
	buffer_load_dwordx4 v154, s[36:39], s89 offen lds
	s_mov_b32 m0, s43
	s_nop 0
	buffer_load_dwordx4 v156, s[36:39], s89 offen lds
	s_mov_b32 m0, s34
	s_nop 0
	buffer_load_dwordx4 v1, s[28:31], s88 offen lds
	s_mov_b32 m0, s44
	s_nop 0
	buffer_load_dwordx4 v155, s[28:31], s88 offen lds
	s_waitcnt vmcnt(8)
	s_waitcnt lgkmcnt(0)
	s_barrier
	s_waitcnt lgkmcnt(0)
	v_mfma_i32_16x16x64_i8 v[62:65], v[134:137], v[178:181], v[62:65]
	v_mfma_i32_16x16x64_i8 v[58:61], v[142:145], v[178:181], v[58:61]
	s_waitcnt lgkmcnt(5)
	v_mfma_i32_16x16x64_i8 v[46:49], v[134:137], v[186:189], v[46:49]
	v_mfma_i32_16x16x64_i8 v[42:45], v[142:145], v[186:189], v[42:45]
	s_waitcnt lgkmcnt(3)
	v_mfma_i32_16x16x64_i8 v[30:33], v[134:137], v[194:197], v[30:33]
	v_mfma_i32_16x16x64_i8 v[26:29], v[142:145], v[194:197], v[26:29]
	s_waitcnt lgkmcnt(1)
	v_mfma_i32_16x16x64_i8 v[14:17], v[134:137], v[202:205], v[14:17]
	v_mfma_i32_16x16x64_i8 v[10:13], v[142:145], v[202:205], v[10:13]
	v_mfma_i32_16x16x64_i8 v[62:65], v[138:141], v[182:185], v[62:65]
	v_mfma_i32_16x16x64_i8 v[58:61], v[146:149], v[182:185], v[58:61]
	v_mfma_i32_16x16x64_i8 v[46:49], v[138:141], v[190:193], v[46:49]
	v_mfma_i32_16x16x64_i8 v[42:45], v[146:149], v[190:193], v[42:45]
	v_mfma_i32_16x16x64_i8 v[30:33], v[138:141], v[198:201], v[30:33]
	v_mfma_i32_16x16x64_i8 v[26:29], v[146:149], v[198:201], v[26:29]
	s_waitcnt lgkmcnt(0)
	v_mfma_i32_16x16x64_i8 v[14:17], v[138:141], v[206:209], v[14:17]
	v_mfma_i32_16x16x64_i8 v[10:13], v[146:149], v[206:209], v[10:13]
	v_mfma_i32_16x16x64_i8 v[54:57], v[150:153], v[178:181], v[54:57]
	v_mfma_i32_16x16x64_i8 v[50:53], v[170:173], v[178:181], v[50:53]
	v_mfma_i32_16x16x64_i8 v[38:41], v[150:153], v[186:189], v[38:41]
	v_mfma_i32_16x16x64_i8 v[34:37], v[170:173], v[186:189], v[34:37]
	v_mfma_i32_16x16x64_i8 v[22:25], v[150:153], v[194:197], v[22:25]
	v_mfma_i32_16x16x64_i8 v[18:21], v[170:173], v[194:197], v[18:21]
	v_mfma_i32_16x16x64_i8 v[6:9], v[150:153], v[202:205], v[6:9]
	v_mfma_i32_16x16x64_i8 v[2:5], v[170:173], v[202:205], v[2:5]
	v_mfma_i32_16x16x64_i8 v[54:57], v[166:169], v[182:185], v[54:57]
	v_mfma_i32_16x16x64_i8 v[50:53], v[174:177], v[182:185], v[50:53]
	v_mfma_i32_16x16x64_i8 v[38:41], v[166:169], v[190:193], v[38:41]
	v_mfma_i32_16x16x64_i8 v[34:37], v[174:177], v[190:193], v[34:37]
	v_mfma_i32_16x16x64_i8 v[22:25], v[166:169], v[198:201], v[22:25]
	v_mfma_i32_16x16x64_i8 v[18:21], v[174:177], v[198:201], v[18:21]
	v_mfma_i32_16x16x64_i8 v[6:9], v[166:169], v[206:209], v[6:9]
	v_mfma_i32_16x16x64_i8 v[2:5], v[174:177], v[206:209], v[2:5]
	s_barrier
	ds_read_b128 v[134:137], v164
	ds_read_b128 v[138:141], v164 offset:1024
	ds_read_b128 v[142:145], v164 offset:2048
	ds_read_b128 v[146:149], v164 offset:3072
	ds_read_b128 v[150:153], v165
	ds_read_b128 v[166:169], v165 offset:1024
	ds_read_b128 v[170:173], v165 offset:2048
	ds_read_b128 v[174:177], v165 offset:3072
	s_add_i32 s88, s88, 0x40000
	s_mov_b32 m0, s45
	ds_read_b128 v[178:181], v163 offset:32768
	ds_read_b128 v[182:185], v163 offset:33792
	ds_read_b128 v[186:189], v163 offset:34816
	ds_read_b128 v[190:193], v163 offset:35840
	ds_read_b128 v[194:197], v163 offset:36864
	ds_read_b128 v[198:201], v163 offset:37888
	ds_read_b128 v[202:205], v163 offset:38912
	ds_read_b128 v[206:209], v163 offset:39936
	buffer_load_dwordx4 v1, s[28:31], s88 offen lds
	s_mov_b32 m0, s47
	s_nop 0
	buffer_load_dwordx4 v155, s[28:31], s88 offen lds
	s_waitcnt vmcnt(8)
	s_waitcnt lgkmcnt(0)
	s_barrier
	s_waitcnt lgkmcnt(0)
	v_mfma_i32_16x16x64_i8 v[126:129], v[134:137], v[178:181], v[126:129]
	v_mfma_i32_16x16x64_i8 v[122:125], v[142:145], v[178:181], v[122:125]
	s_waitcnt lgkmcnt(5)
	v_mfma_i32_16x16x64_i8 v[110:113], v[134:137], v[186:189], v[110:113]
	v_mfma_i32_16x16x64_i8 v[106:109], v[142:145], v[186:189], v[106:109]
	s_waitcnt lgkmcnt(3)
	v_mfma_i32_16x16x64_i8 v[94:97], v[134:137], v[194:197], v[94:97]
	v_mfma_i32_16x16x64_i8 v[90:93], v[142:145], v[194:197], v[90:93]
	s_waitcnt lgkmcnt(1)
	v_mfma_i32_16x16x64_i8 v[78:81], v[134:137], v[202:205], v[78:81]
	v_mfma_i32_16x16x64_i8 v[74:77], v[142:145], v[202:205], v[74:77]
	v_mfma_i32_16x16x64_i8 v[126:129], v[138:141], v[182:185], v[126:129]
	v_mfma_i32_16x16x64_i8 v[122:125], v[146:149], v[182:185], v[122:125]
	v_mfma_i32_16x16x64_i8 v[110:113], v[138:141], v[190:193], v[110:113]
	v_mfma_i32_16x16x64_i8 v[106:109], v[146:149], v[190:193], v[106:109]
	v_mfma_i32_16x16x64_i8 v[94:97], v[138:141], v[198:201], v[94:97]
	v_mfma_i32_16x16x64_i8 v[90:93], v[146:149], v[198:201], v[90:93]
	s_waitcnt lgkmcnt(0)
	v_mfma_i32_16x16x64_i8 v[78:81], v[138:141], v[206:209], v[78:81]
	v_mfma_i32_16x16x64_i8 v[74:77], v[146:149], v[206:209], v[74:77]
	v_mfma_i32_16x16x64_i8 v[118:121], v[150:153], v[178:181], v[118:121]
	v_mfma_i32_16x16x64_i8 v[114:117], v[170:173], v[178:181], v[114:117]
	v_mfma_i32_16x16x64_i8 v[102:105], v[150:153], v[186:189], v[102:105]
	v_mfma_i32_16x16x64_i8 v[98:101], v[170:173], v[186:189], v[98:101]
	v_mfma_i32_16x16x64_i8 v[86:89], v[150:153], v[194:197], v[86:89]
	v_mfma_i32_16x16x64_i8 v[82:85], v[170:173], v[194:197], v[82:85]
	v_mfma_i32_16x16x64_i8 v[70:73], v[150:153], v[202:205], v[70:73]
	v_mfma_i32_16x16x64_i8 v[66:69], v[170:173], v[202:205], v[66:69]
	v_mfma_i32_16x16x64_i8 v[118:121], v[166:169], v[182:185], v[118:121]
	v_mfma_i32_16x16x64_i8 v[114:117], v[174:177], v[182:185], v[114:117]
	v_mfma_i32_16x16x64_i8 v[102:105], v[166:169], v[190:193], v[102:105]
	v_mfma_i32_16x16x64_i8 v[98:101], v[174:177], v[190:193], v[98:101]
	v_mfma_i32_16x16x64_i8 v[86:89], v[166:169], v[198:201], v[86:89]
	v_mfma_i32_16x16x64_i8 v[82:85], v[174:177], v[198:201], v[82:85]
	v_mfma_i32_16x16x64_i8 v[70:73], v[166:169], v[206:209], v[70:73]
	v_mfma_i32_16x16x64_i8 v[66:69], v[174:177], v[206:209], v[66:69]
	s_barrier
	s_mov_b32 m0, s48
	s_or_b32 s88, s83, 0x80
	ds_read_b128 v[178:181], v163 offset:49152
	ds_read_b128 v[182:185], v163 offset:50176
	ds_read_b128 v[186:189], v163 offset:51200
	ds_read_b128 v[190:193], v163 offset:52224
	ds_read_b128 v[194:197], v163 offset:53248
	ds_read_b128 v[198:201], v163 offset:54272
	ds_read_b128 v[202:205], v163 offset:55296
	ds_read_b128 v[206:209], v163 offset:56320
	buffer_load_dwordx4 v154, s[36:39], s88 offen lds
	s_mov_b32 m0, s49
	s_add_i32 s83, s83, 0x40080
	buffer_load_dwordx4 v156, s[36:39], s88 offen lds
	s_mov_b32 m0, s53
	s_nop 0
	buffer_load_dwordx4 v154, s[36:39], s83 offen lds
	s_mov_b32 m0, s55
	s_nop 0
	buffer_load_dwordx4 v156, s[36:39], s83 offen lds
	s_mov_b32 m0, s51
	s_nop 0
	buffer_load_dwordx4 v1, s[28:31], s82 offen lds
	s_mov_b32 m0, s52
	s_nop 0
	buffer_load_dwordx4 v155, s[28:31], s82 offen lds
	s_waitcnt vmcnt(8)
	s_waitcnt lgkmcnt(0)
	s_barrier
	s_waitcnt lgkmcnt(0)
	v_mfma_i32_16x16x64_i8 v[62:65], v[134:137], v[178:181], v[62:65]
	v_mfma_i32_16x16x64_i8 v[58:61], v[142:145], v[178:181], v[58:61]
	s_waitcnt lgkmcnt(5)
	v_mfma_i32_16x16x64_i8 v[46:49], v[134:137], v[186:189], v[46:49]
	v_mfma_i32_16x16x64_i8 v[42:45], v[142:145], v[186:189], v[42:45]
	s_waitcnt lgkmcnt(3)
	v_mfma_i32_16x16x64_i8 v[30:33], v[134:137], v[194:197], v[30:33]
	v_mfma_i32_16x16x64_i8 v[26:29], v[142:145], v[194:197], v[26:29]
	s_waitcnt lgkmcnt(1)
	v_mfma_i32_16x16x64_i8 v[14:17], v[134:137], v[202:205], v[14:17]
	v_mfma_i32_16x16x64_i8 v[10:13], v[142:145], v[202:205], v[10:13]
	v_mfma_i32_16x16x64_i8 v[62:65], v[138:141], v[182:185], v[62:65]
	v_mfma_i32_16x16x64_i8 v[58:61], v[146:149], v[182:185], v[58:61]
	v_mfma_i32_16x16x64_i8 v[46:49], v[138:141], v[190:193], v[46:49]
	v_mfma_i32_16x16x64_i8 v[42:45], v[146:149], v[190:193], v[42:45]
	v_mfma_i32_16x16x64_i8 v[30:33], v[138:141], v[198:201], v[30:33]
	v_mfma_i32_16x16x64_i8 v[26:29], v[146:149], v[198:201], v[26:29]
	s_waitcnt lgkmcnt(0)
	v_mfma_i32_16x16x64_i8 v[14:17], v[138:141], v[206:209], v[14:17]
	v_mfma_i32_16x16x64_i8 v[10:13], v[146:149], v[206:209], v[10:13]
	v_mfma_i32_16x16x64_i8 v[54:57], v[150:153], v[178:181], v[54:57]
	v_mfma_i32_16x16x64_i8 v[50:53], v[170:173], v[178:181], v[50:53]
	v_mfma_i32_16x16x64_i8 v[38:41], v[150:153], v[186:189], v[38:41]
	v_mfma_i32_16x16x64_i8 v[34:37], v[170:173], v[186:189], v[34:37]
	v_mfma_i32_16x16x64_i8 v[22:25], v[150:153], v[194:197], v[22:25]
	v_mfma_i32_16x16x64_i8 v[18:21], v[170:173], v[194:197], v[18:21]
	v_mfma_i32_16x16x64_i8 v[6:9], v[150:153], v[202:205], v[6:9]
	v_mfma_i32_16x16x64_i8 v[2:5], v[170:173], v[202:205], v[2:5]
	v_mfma_i32_16x16x64_i8 v[54:57], v[166:169], v[182:185], v[54:57]
	v_mfma_i32_16x16x64_i8 v[50:53], v[174:177], v[182:185], v[50:53]
	v_mfma_i32_16x16x64_i8 v[38:41], v[166:169], v[190:193], v[38:41]
	v_mfma_i32_16x16x64_i8 v[34:37], v[174:177], v[190:193], v[34:37]
	v_mfma_i32_16x16x64_i8 v[22:25], v[166:169], v[198:201], v[22:25]
	v_mfma_i32_16x16x64_i8 v[18:21], v[174:177], v[198:201], v[18:21]
	v_mfma_i32_16x16x64_i8 v[6:9], v[166:169], v[206:209], v[6:9]
	v_mfma_i32_16x16x64_i8 v[2:5], v[174:177], v[206:209], v[2:5]
	s_barrier
	s_add_i32 s80, s80, 2
	s_addk_i32 s78, 0x100
	s_addk_i32 s79, 0x100
	s_cmp_gt_u32 s80, 13
	s_cbranch_scc0 .LBB0_289
	s_and_b64 vcc, exec, s[16:17]
	s_cbranch_vccz .LBB0_292
	s_barrier

.LBB0_299:
	s_waitcnt vmcnt(0)
	s_barrier
	s_setprio 0
	s_load_dwordx4 s[60:63], s[0:1], 0x88
